# adds single-column long-conv groups: B read first, resident-A MFMA first
# baseline (speedup 1.0000x reference)
; #define MFMA(a, b, c) __builtin_amdgcn_mfma_f32_32x32x16_bf16((a), (b), (c), 0, 0, 0)
; __device__ __forceinline__ void toeplitz_item(const Params& p, int layer, int half, int c, bf16* sm, int dry, unsigned* done_ctr) {
;     ...
;       for (int ni = 0; ni < 2; ++ni) {
;         const int nlo = 32 * wn + 64 * ni;
;         actv[ni] = half ? true : !((nlo + 31 - D < 0) || (nlo - D >= 128));
;         const int n = nlo + r;
;         const int src = n - D;
;         const bool valid = half ? ((unsigned)((n & 15) - D) < 16u) : ((unsigned)src < 128u);
;         bblk[ni] = valid ? src : 128;
;       }
;       if (!actv[0] && !actv[1]) continue;
;       const int tb = 16 * (3 - Dl) + 16 + hh - rt;
;       const bf16* ap0 = sW + (aq * 83 + tb - 4 * (2 * wm)) * 8;
;       const bf16* bp0 = sU + bblk[0] * 136 + 8 * hh;
;       const bf16* bp1 = sU + bblk[1] * 136 + 8 * hh;
;       if (actv[0] && actv[1]) {
; #pragma unroll
;         for (int ks = 0; ks < 8; ++ks) {
;           const s8v a0 = *(const s8v*)(ap0 + 16 * ks), a1 = *(const s8v*)(ap0 - 32 + 16 * ks);
;           const s8v b0 = *(const s8v*)(bp0 + 16 * ks), b1 = *(const s8v*)(bp1 + 16 * ks);
;           acc[0][0] = MFMA(a0, b0, acc[0][0]);
;           acc[1][0] = MFMA(a1, b0, acc[1][0]);
;           acc[0][1] = MFMA(a0, b1, acc[0][1]);
;           acc[1][1] = MFMA(a1, b1, acc[1][1]);
;         }
.LBB0_1147:
	s_or_b64 exec, exec, s[2:3]
	v_add_u32_e32 v66, 3, v123
	v_add_u32_e32 v124, s74, v122
	v_cmp_gt_u32_e64 s[2:3], 16, v66
	v_add_u32_e32 v66, 0x1100, v124
	ds_read_b128 v[70:73], v89 offset:35088
	v_cndmask_b32_e64 v66, v228, v66, s[2:3]
	v_add_u32_e32 v125, v90, v66
	ds_read_b128 v[66:69], v89 offset:35024
	ds_read_b128 v[74:77], v125
	v_add_u32_e32 v78, 0x5500, v124
	s_waitcnt lgkmcnt(0)
	v_mfma_f32_32x32x16_bf16 v[50:65], v[70:73], v[74:77], v[50:65]
	s_addk_i32 s74, 0xfbc0
	s_cmpk_eq_i32 s74, 0xe240
	v_mfma_f32_32x32x16_bf16 v[18:33], v[66:69], v[74:77], v[18:33]
	v_cndmask_b32_e64 v74, v228, v78, s[2:3]
	v_add_u32_e32 v134, v90, v74
	ds_read_b128 v[74:77], v134
	ds_read_b128 v[78:81], v89 offset:35120
	ds_read_b128 v[126:129], v125 offset:32
	s_waitcnt lgkmcnt(2)
	v_mfma_f32_32x32x16_bf16 v[34:49], v[70:73], v[74:77], v[34:49]
	v_mfma_f32_32x32x16_bf16 v[2:17], v[66:69], v[74:77], v[2:17]
	ds_read_b128 v[74:77], v89 offset:35056
	s_waitcnt lgkmcnt(1)
	v_mfma_f32_32x32x16_bf16 v[50:65], v[78:81], v[126:129], v[50:65]
	s_waitcnt lgkmcnt(0)
	v_mfma_f32_32x32x16_bf16 v[18:33], v[74:77], v[126:129], v[18:33]
	ds_read_b128 v[126:129], v134 offset:32
	s_waitcnt lgkmcnt(0)
	v_mfma_f32_32x32x16_bf16 v[34:49], v[78:81], v[126:129], v[34:49]
	v_mfma_f32_32x32x16_bf16 v[2:17], v[74:77], v[126:129], v[2:17]
	ds_read_b128 v[130:133], v125 offset:64
	ds_read_b128 v[200:203], v134 offset:64
	ds_read_b128 v[126:129], v89 offset:35152
	ds_read_b128 v[204:207], v125 offset:96
	ds_read_b128 v[208:211], v134 offset:96
	s_waitcnt lgkmcnt(4)
	v_mfma_f32_32x32x16_bf16 v[18:33], v[70:73], v[130:133], v[18:33]
	s_waitcnt lgkmcnt(3)
	v_mfma_f32_32x32x16_bf16 v[2:17], v[70:73], v[200:203], v[2:17]
	ds_read_b128 v[70:73], v89 offset:35184
	s_waitcnt lgkmcnt(3)
	v_mfma_f32_32x32x16_bf16 v[50:65], v[126:129], v[130:133], v[50:65]
	v_mfma_f32_32x32x16_bf16 v[34:49], v[126:129], v[200:203], v[34:49]
	ds_read_b128 v[130:133], v125 offset:128
	ds_read_b128 v[200:203], v134 offset:128
	s_waitcnt lgkmcnt(4)
	v_mfma_f32_32x32x16_bf16 v[18:33], v[78:81], v[204:207], v[18:33]
	s_waitcnt lgkmcnt(3)
	v_mfma_f32_32x32x16_bf16 v[2:17], v[78:81], v[208:211], v[2:17]
	ds_read_b128 v[78:81], v89 offset:35216
	s_waitcnt lgkmcnt(3)
	v_mfma_f32_32x32x16_bf16 v[50:65], v[70:73], v[204:207], v[50:65]
	v_mfma_f32_32x32x16_bf16 v[34:49], v[70:73], v[208:211], v[34:49]
	ds_read_b128 v[204:207], v125 offset:160
	ds_read_b128 v[208:211], v134 offset:160
	s_waitcnt lgkmcnt(4)
	v_mfma_f32_32x32x16_bf16 v[18:33], v[126:129], v[130:133], v[18:33]
	s_waitcnt lgkmcnt(3)
	v_mfma_f32_32x32x16_bf16 v[2:17], v[126:129], v[200:203], v[2:17]
	ds_read_b128 v[126:129], v89 offset:35248
	s_waitcnt lgkmcnt(3)
	v_mfma_f32_32x32x16_bf16 v[50:65], v[78:81], v[130:133], v[50:65]
	v_mfma_f32_32x32x16_bf16 v[34:49], v[78:81], v[200:203], v[34:49]
	ds_read_b128 v[130:133], v125 offset:192
	ds_read_b128 v[200:203], v134 offset:192
	s_waitcnt lgkmcnt(4)
	v_mfma_f32_32x32x16_bf16 v[18:33], v[70:73], v[204:207], v[18:33]
	s_waitcnt lgkmcnt(3)
	v_mfma_f32_32x32x16_bf16 v[2:17], v[70:73], v[208:211], v[2:17]
	ds_read_b128 v[70:73], v89 offset:35280
	s_waitcnt lgkmcnt(3)
	v_mfma_f32_32x32x16_bf16 v[50:65], v[126:129], v[204:207], v[50:65]
	v_mfma_f32_32x32x16_bf16 v[34:49], v[126:129], v[208:211], v[34:49]
	s_waitcnt lgkmcnt(2)
	v_mfma_f32_32x32x16_bf16 v[18:33], v[78:81], v[130:133], v[18:33]
	s_waitcnt lgkmcnt(1)
	v_mfma_f32_32x32x16_bf16 v[2:17], v[78:81], v[200:203], v[2:17]
	s_waitcnt lgkmcnt(0)
	v_mfma_f32_32x32x16_bf16 v[50:65], v[70:73], v[130:133], v[50:65]
	v_mfma_f32_32x32x16_bf16 v[34:49], v[70:73], v[200:203], v[34:49]
	ds_read_b128 v[70:73], v89 offset:35312
	ds_read_b128 v[78:81], v125 offset:224
	v_add_u32_e32 v130, 0x53f0, v124
	s_waitcnt lgkmcnt(0)
	v_mfma_f32_32x32x16_bf16 v[50:65], v[70:73], v[78:81], v[50:65]
	v_mfma_f32_32x32x16_bf16 v[18:33], v[126:129], v[78:81], v[18:33]
	ds_read_b128 v[78:81], v134 offset:224
	s_waitcnt lgkmcnt(0)
	v_mfma_f32_32x32x16_bf16 v[34:49], v[70:73], v[78:81], v[34:49]
	v_add_u32_e32 v70, 2, v123
	v_cmp_gt_u32_e64 s[2:3], 16, v70
	v_add_u32_e32 v70, 0xff0, v124
	s_nop 0
	v_cndmask_b32_e64 v70, v228, v70, s[2:3]
	v_add_u32_e32 v125, v90, v70
	ds_read_b128 v[70:73], v89 offset:34768
	v_mfma_f32_32x32x16_bf16 v[2:17], v[126:129], v[78:81], v[2:17]
	ds_read_b128 v[78:81], v125
	ds_read_b128 v[126:129], v89 offset:34832
	s_waitcnt lgkmcnt(1)
	v_mfma_f32_32x32x16_bf16 v[18:33], v[70:73], v[78:81], v[18:33]
	s_waitcnt lgkmcnt(0)
	v_mfma_f32_32x32x16_bf16 v[50:65], v[126:129], v[78:81], v[50:65]
	v_cndmask_b32_e64 v78, v228, v130, s[2:3]
	v_add_u32_e32 v142, v90, v78
	ds_read_b128 v[78:81], v142
	ds_read_b128 v[130:133], v89 offset:34864
	ds_read_b128 v[134:137], v125 offset:32
	s_waitcnt lgkmcnt(2)
	v_mfma_f32_32x32x16_bf16 v[34:49], v[126:129], v[78:81], v[34:49]
	v_mfma_f32_32x32x16_bf16 v[2:17], v[70:73], v[78:81], v[2:17]
	ds_read_b128 v[78:81], v89 offset:34800
	s_waitcnt lgkmcnt(1)
	v_mfma_f32_32x32x16_bf16 v[50:65], v[130:133], v[134:137], v[50:65]
	s_waitcnt lgkmcnt(0)
	v_mfma_f32_32x32x16_bf16 v[18:33], v[78:81], v[134:137], v[18:33]
	ds_read_b128 v[134:137], v142 offset:32
	s_waitcnt lgkmcnt(0)
	v_mfma_f32_32x32x16_bf16 v[34:49], v[130:133], v[134:137], v[34:49]
	v_mfma_f32_32x32x16_bf16 v[2:17], v[78:81], v[134:137], v[2:17]
	ds_read_b128 v[138:141], v125 offset:64
	ds_read_b128 v[200:203], v142 offset:64
	ds_read_b128 v[134:137], v89 offset:34896
	ds_read_b128 v[204:207], v125 offset:96
	ds_read_b128 v[208:211], v142 offset:96
	s_waitcnt lgkmcnt(4)
	v_mfma_f32_32x32x16_bf16 v[18:33], v[126:129], v[138:141], v[18:33]
	s_waitcnt lgkmcnt(3)
; #define MFMA(a, b, c) __builtin_amdgcn_mfma_f32_32x32x16_bf16((a), (b), (c), 0, 0, 0)
; __device__ __forceinline__ void toeplitz_item(const Params& p, int layer, int half, int c, bf16* sm, int dry, unsigned* done_ctr) {
;     ...
;       if (actv[0] && actv[1]) {
; #pragma unroll
;         for (int ks = 0; ks < 8; ++ks) {
;           const s8v a0 = *(const s8v*)(ap0 + 16 * ks), a1 = *(const s8v*)(ap0 - 32 + 16 * ks);
;           const s8v b0 = *(const s8v*)(bp0 + 16 * ks), b1 = *(const s8v*)(bp1 + 16 * ks);
;           acc[0][0] = MFMA(a0, b0, acc[0][0]);
;           acc[1][0] = MFMA(a1, b0, acc[1][0]);
;           acc[0][1] = MFMA(a0, b1, acc[0][1]);
;           acc[1][1] = MFMA(a1, b1, acc[1][1]);
;         }
	v_mfma_f32_32x32x16_bf16 v[2:17], v[126:129], v[200:203], v[2:17]
	ds_read_b128 v[126:129], v89 offset:34928
	s_waitcnt lgkmcnt(3)
	v_mfma_f32_32x32x16_bf16 v[50:65], v[134:137], v[138:141], v[50:65]
	v_mfma_f32_32x32x16_bf16 v[34:49], v[134:137], v[200:203], v[34:49]
	ds_read_b128 v[138:141], v125 offset:128
	ds_read_b128 v[200:203], v142 offset:128
	s_waitcnt lgkmcnt(4)
	v_mfma_f32_32x32x16_bf16 v[18:33], v[130:133], v[204:207], v[18:33]
	s_waitcnt lgkmcnt(3)
	v_mfma_f32_32x32x16_bf16 v[2:17], v[130:133], v[208:211], v[2:17]
	ds_read_b128 v[130:133], v89 offset:34960
	s_waitcnt lgkmcnt(3)
	v_mfma_f32_32x32x16_bf16 v[50:65], v[126:129], v[204:207], v[50:65]
	v_mfma_f32_32x32x16_bf16 v[34:49], v[126:129], v[208:211], v[34:49]
	s_waitcnt lgkmcnt(2)
	v_mfma_f32_32x32x16_bf16 v[18:33], v[134:137], v[138:141], v[18:33]
	s_waitcnt lgkmcnt(1)
	v_mfma_f32_32x32x16_bf16 v[2:17], v[134:137], v[200:203], v[2:17]
	s_waitcnt lgkmcnt(0)
	v_mfma_f32_32x32x16_bf16 v[50:65], v[130:133], v[138:141], v[50:65]
	v_mfma_f32_32x32x16_bf16 v[34:49], v[130:133], v[200:203], v[34:49]
	ds_read_b128 v[138:141], v125 offset:160
	ds_read_b128 v[134:137], v89 offset:34992
	s_waitcnt lgkmcnt(1)
	v_mfma_f32_32x32x16_bf16 v[18:33], v[126:129], v[138:141], v[18:33]
	s_waitcnt lgkmcnt(0)
	v_mfma_f32_32x32x16_bf16 v[50:65], v[134:137], v[138:141], v[50:65]
	ds_read_b128 v[138:141], v142 offset:160
	s_waitcnt lgkmcnt(0)
	v_mfma_f32_32x32x16_bf16 v[2:17], v[126:129], v[138:141], v[2:17]
	ds_read_b128 v[126:129], v125 offset:192
	v_mfma_f32_32x32x16_bf16 v[34:49], v[134:137], v[138:141], v[34:49]
	s_waitcnt lgkmcnt(0)
	v_mfma_f32_32x32x16_bf16 v[50:65], v[66:69], v[126:129], v[50:65]
	v_mfma_f32_32x32x16_bf16 v[18:33], v[130:133], v[126:129], v[18:33]
	ds_read_b128 v[126:129], v142 offset:192
	s_waitcnt lgkmcnt(0)
	v_mfma_f32_32x32x16_bf16 v[34:49], v[66:69], v[126:129], v[34:49]
	ds_read_b128 v[66:69], v125 offset:224
	v_mfma_f32_32x32x16_bf16 v[2:17], v[130:133], v[126:129], v[2:17]
	ds_read_b128 v[126:129], v89 offset:34576
	v_add_u32_e32 v130, 0x52e0, v124
	s_waitcnt lgkmcnt(1)
	v_mfma_f32_32x32x16_bf16 v[50:65], v[74:77], v[66:69], v[50:65]
	v_mfma_f32_32x32x16_bf16 v[18:33], v[134:137], v[66:69], v[18:33]
	ds_read_b128 v[66:69], v142 offset:224
	s_waitcnt lgkmcnt(0)
	v_mfma_f32_32x32x16_bf16 v[34:49], v[74:77], v[66:69], v[34:49]
	v_mfma_f32_32x32x16_bf16 v[2:17], v[134:137], v[66:69], v[2:17]
	v_add_u32_e32 v66, 1, v123
	v_cmp_gt_u32_e64 s[2:3], 16, v66
	v_add_u32_e32 v66, 0xee0, v124
	s_nop 0
	v_cndmask_b32_e64 v66, v228, v66, s[2:3]
	v_add_u32_e32 v125, v90, v66
	ds_read_b128 v[66:69], v89 offset:34512
	ds_read_b128 v[74:77], v125
	s_waitcnt lgkmcnt(0)
	v_mfma_f32_32x32x16_bf16 v[50:65], v[126:129], v[74:77], v[50:65]
	v_mfma_f32_32x32x16_bf16 v[18:33], v[66:69], v[74:77], v[18:33]
	v_cndmask_b32_e64 v74, v228, v130, s[2:3]
	v_add_u32_e32 v142, v90, v74
	ds_read_b128 v[74:77], v142
	ds_read_b128 v[130:133], v89 offset:34608
	ds_read_b128 v[134:137], v125 offset:32
	v_cmp_gt_u32_e64 s[2:3], 16, v123
	v_add_u32_e32 v123, -4, v123
	s_waitcnt lgkmcnt(2)
	v_mfma_f32_32x32x16_bf16 v[34:49], v[126:129], v[74:77], v[34:49]
	v_mfma_f32_32x32x16_bf16 v[2:17], v[66:69], v[74:77], v[2:17]
	ds_read_b128 v[74:77], v89 offset:34544
	s_waitcnt lgkmcnt(1)
	v_mfma_f32_32x32x16_bf16 v[50:65], v[130:133], v[134:137], v[50:65]
	s_waitcnt lgkmcnt(0)
	v_mfma_f32_32x32x16_bf16 v[18:33], v[74:77], v[134:137], v[18:33]
	ds_read_b128 v[134:137], v142 offset:32
	s_waitcnt lgkmcnt(0)
	v_mfma_f32_32x32x16_bf16 v[34:49], v[130:133], v[134:137], v[34:49]
	v_mfma_f32_32x32x16_bf16 v[2:17], v[74:77], v[134:137], v[2:17]
	ds_read_b128 v[138:141], v125 offset:64
	ds_read_b128 v[200:203], v142 offset:64
	ds_read_b128 v[134:137], v89 offset:34640
	ds_read_b128 v[204:207], v125 offset:96
	ds_read_b128 v[208:211], v142 offset:96
	s_waitcnt lgkmcnt(4)
	v_mfma_f32_32x32x16_bf16 v[18:33], v[126:129], v[138:141], v[18:33]
	s_waitcnt lgkmcnt(3)
	v_mfma_f32_32x32x16_bf16 v[2:17], v[126:129], v[200:203], v[2:17]
	ds_read_b128 v[126:129], v89 offset:34672
	s_waitcnt lgkmcnt(3)
	v_mfma_f32_32x32x16_bf16 v[50:65], v[134:137], v[138:141], v[50:65]
	v_mfma_f32_32x32x16_bf16 v[34:49], v[134:137], v[200:203], v[34:49]
	ds_read_b128 v[138:141], v125 offset:128
	ds_read_b128 v[200:203], v142 offset:128
	s_waitcnt lgkmcnt(4)
	v_mfma_f32_32x32x16_bf16 v[18:33], v[130:133], v[204:207], v[18:33]
	s_waitcnt lgkmcnt(3)
	v_mfma_f32_32x32x16_bf16 v[2:17], v[130:133], v[208:211], v[2:17]
	ds_read_b128 v[130:133], v89 offset:34704
	s_waitcnt lgkmcnt(3)
	v_mfma_f32_32x32x16_bf16 v[50:65], v[126:129], v[204:207], v[50:65]
	v_mfma_f32_32x32x16_bf16 v[34:49], v[126:129], v[208:211], v[34:49]
	s_waitcnt lgkmcnt(2)
	v_mfma_f32_32x32x16_bf16 v[18:33], v[134:137], v[138:141], v[18:33]
	s_waitcnt lgkmcnt(1)
	v_mfma_f32_32x32x16_bf16 v[2:17], v[134:137], v[200:203], v[2:17]
	s_waitcnt lgkmcnt(0)
	v_mfma_f32_32x32x16_bf16 v[50:65], v[130:133], v[138:141], v[50:65]
	v_mfma_f32_32x32x16_bf16 v[34:49], v[130:133], v[200:203], v[34:49]
	ds_read_b128 v[138:141], v125 offset:160
	ds_read_b128 v[134:137], v89 offset:34736
	s_waitcnt lgkmcnt(1)
; #define MFMA(a, b, c) __builtin_amdgcn_mfma_f32_32x32x16_bf16((a), (b), (c), 0, 0, 0)
; __device__ __forceinline__ void toeplitz_item(const Params& p, int layer, int half, int c, bf16* sm, int dry, unsigned* done_ctr) {
;     ...
;       if (actv[0] && actv[1]) {
; #pragma unroll
;         for (int ks = 0; ks < 8; ++ks) {
;           const s8v a0 = *(const s8v*)(ap0 + 16 * ks), a1 = *(const s8v*)(ap0 - 32 + 16 * ks);
;           const s8v b0 = *(const s8v*)(bp0 + 16 * ks), b1 = *(const s8v*)(bp1 + 16 * ks);
;           acc[0][0] = MFMA(a0, b0, acc[0][0]);
;           acc[1][0] = MFMA(a1, b0, acc[1][0]);
;           acc[0][1] = MFMA(a0, b1, acc[0][1]);
;           acc[1][1] = MFMA(a1, b1, acc[1][1]);
;         }
	v_mfma_f32_32x32x16_bf16 v[18:33], v[126:129], v[138:141], v[18:33]
	s_waitcnt lgkmcnt(0)
	v_mfma_f32_32x32x16_bf16 v[50:65], v[134:137], v[138:141], v[50:65]
	ds_read_b128 v[138:141], v142 offset:160
	s_waitcnt lgkmcnt(0)
	v_mfma_f32_32x32x16_bf16 v[2:17], v[126:129], v[138:141], v[2:17]
	ds_read_b128 v[126:129], v125 offset:192
	v_mfma_f32_32x32x16_bf16 v[34:49], v[134:137], v[138:141], v[34:49]
	s_waitcnt lgkmcnt(0)
	v_mfma_f32_32x32x16_bf16 v[50:65], v[70:73], v[126:129], v[50:65]
	v_mfma_f32_32x32x16_bf16 v[18:33], v[130:133], v[126:129], v[18:33]
	ds_read_b128 v[126:129], v142 offset:192
	s_waitcnt lgkmcnt(0)
	v_mfma_f32_32x32x16_bf16 v[34:49], v[70:73], v[126:129], v[34:49]
	ds_read_b128 v[70:73], v125 offset:224
	v_mfma_f32_32x32x16_bf16 v[2:17], v[130:133], v[126:129], v[2:17]
	ds_read_b128 v[126:129], v89 offset:34256
	s_waitcnt lgkmcnt(1)
	v_mfma_f32_32x32x16_bf16 v[50:65], v[78:81], v[70:73], v[50:65]
	v_mfma_f32_32x32x16_bf16 v[18:33], v[134:137], v[70:73], v[18:33]
	ds_read_b128 v[70:73], v142 offset:224
	s_waitcnt lgkmcnt(0)
	v_mfma_f32_32x32x16_bf16 v[34:49], v[78:81], v[70:73], v[34:49]
	v_add_u32_e32 v78, 0xdd0, v124
	v_cndmask_b32_e64 v78, v228, v78, s[2:3]
	v_add_u32_e32 v132, v90, v78
	ds_read_b128 v[78:81], v132
	v_add_u32_e32 v124, 0x51d0, v124
	v_mfma_f32_32x32x16_bf16 v[2:17], v[134:137], v[70:73], v[2:17]
	ds_read_b128 v[70:73], v89 offset:34320
	s_waitcnt lgkmcnt(0)
	v_mfma_f32_32x32x16_bf16 v[50:65], v[70:73], v[78:81], v[50:65]
	v_mfma_f32_32x32x16_bf16 v[18:33], v[126:129], v[78:81], v[18:33]
	v_cndmask_b32_e64 v78, v228, v124, s[2:3]
	v_add_u32_e32 v133, v90, v78
	ds_read_b128 v[78:81], v133
	s_movk_i32 s2, 0xfc00
	s_mov_b32 s3, -1
	v_lshl_add_u64 v[82:83], v[82:83], 0, s[2:3]
	v_lshl_add_u64 v[84:85], v[84:85], 0, s[2:3]
	s_waitcnt lgkmcnt(0)
	v_mfma_f32_32x32x16_bf16 v[34:49], v[70:73], v[78:81], v[34:49]
	v_lshl_add_u64 v[86:87], v[86:87], 0, s[2:3]
	v_mfma_f32_32x32x16_bf16 v[2:17], v[126:129], v[78:81], v[2:17]
	ds_read_b128 v[78:81], v89 offset:34352
	ds_read_b128 v[124:127], v132 offset:32
	ds_read_b128 v[128:131], v89 offset:34288
	s_waitcnt lgkmcnt(1)
	v_mfma_f32_32x32x16_bf16 v[50:65], v[78:81], v[124:127], v[50:65]
	s_waitcnt lgkmcnt(0)
	v_mfma_f32_32x32x16_bf16 v[18:33], v[128:131], v[124:127], v[18:33]
	ds_read_b128 v[124:127], v133 offset:32
	s_waitcnt lgkmcnt(0)
	v_mfma_f32_32x32x16_bf16 v[34:49], v[78:81], v[124:127], v[34:49]
	v_mfma_f32_32x32x16_bf16 v[2:17], v[128:131], v[124:127], v[2:17]
	ds_read_b128 v[128:131], v132 offset:64
	ds_read_b128 v[200:203], v133 offset:64
	ds_read_b128 v[124:127], v89 offset:34384
	ds_read_b128 v[204:207], v132 offset:96
	ds_read_b128 v[208:211], v133 offset:96
	s_waitcnt lgkmcnt(4)
	v_mfma_f32_32x32x16_bf16 v[18:33], v[70:73], v[128:131], v[18:33]
	s_waitcnt lgkmcnt(3)
	v_mfma_f32_32x32x16_bf16 v[2:17], v[70:73], v[200:203], v[2:17]
	ds_read_b128 v[70:73], v89 offset:34416
	s_waitcnt lgkmcnt(3)
	v_mfma_f32_32x32x16_bf16 v[50:65], v[124:127], v[128:131], v[50:65]
	v_mfma_f32_32x32x16_bf16 v[34:49], v[124:127], v[200:203], v[34:49]
	ds_read_b128 v[128:131], v132 offset:128
	ds_read_b128 v[200:203], v133 offset:128
	s_waitcnt lgkmcnt(4)
	v_mfma_f32_32x32x16_bf16 v[18:33], v[78:81], v[204:207], v[18:33]
	s_waitcnt lgkmcnt(3)
	v_mfma_f32_32x32x16_bf16 v[2:17], v[78:81], v[208:211], v[2:17]
	ds_read_b128 v[78:81], v89 offset:34448
	s_waitcnt lgkmcnt(3)
	v_mfma_f32_32x32x16_bf16 v[50:65], v[70:73], v[204:207], v[50:65]
	v_mfma_f32_32x32x16_bf16 v[34:49], v[70:73], v[208:211], v[34:49]
	s_waitcnt lgkmcnt(2)
	v_mfma_f32_32x32x16_bf16 v[18:33], v[124:127], v[128:131], v[18:33]
	s_waitcnt lgkmcnt(1)
	v_mfma_f32_32x32x16_bf16 v[2:17], v[124:127], v[200:203], v[2:17]
	s_waitcnt lgkmcnt(0)
	v_mfma_f32_32x32x16_bf16 v[50:65], v[78:81], v[128:131], v[50:65]
	v_mfma_f32_32x32x16_bf16 v[34:49], v[78:81], v[200:203], v[34:49]
	ds_read_b128 v[128:131], v132 offset:160
	ds_read_b128 v[124:127], v89 offset:34480
	s_waitcnt lgkmcnt(1)
	v_mfma_f32_32x32x16_bf16 v[18:33], v[70:73], v[128:131], v[18:33]
	s_waitcnt lgkmcnt(0)
	v_mfma_f32_32x32x16_bf16 v[50:65], v[124:127], v[128:131], v[50:65]
	ds_read_b128 v[128:131], v133 offset:160
	s_waitcnt lgkmcnt(0)
	v_mfma_f32_32x32x16_bf16 v[2:17], v[70:73], v[128:131], v[2:17]
	ds_read_b128 v[70:73], v132 offset:192
	v_mfma_f32_32x32x16_bf16 v[34:49], v[124:127], v[128:131], v[34:49]
	s_waitcnt lgkmcnt(0)
	v_mfma_f32_32x32x16_bf16 v[50:65], v[66:69], v[70:73], v[50:65]
	v_mfma_f32_32x32x16_bf16 v[18:33], v[78:81], v[70:73], v[18:33]
	ds_read_b128 v[70:73], v133 offset:192
	s_waitcnt lgkmcnt(0)
	v_mfma_f32_32x32x16_bf16 v[34:49], v[66:69], v[70:73], v[34:49]
	ds_read_b128 v[66:69], v132 offset:224
	v_mfma_f32_32x32x16_bf16 v[2:17], v[78:81], v[70:73], v[2:17]
	s_waitcnt lgkmcnt(0)
	v_mfma_f32_32x32x16_bf16 v[50:65], v[74:77], v[66:69], v[50:65]
	v_mfma_f32_32x32x16_bf16 v[18:33], v[124:127], v[66:69], v[18:33]
	ds_read_b128 v[66:69], v133 offset:224
	s_waitcnt lgkmcnt(0)
	v_mfma_f32_32x32x16_bf16 v[34:49], v[74:77], v[66:69], v[34:49]
	v_mfma_f32_32x32x16_bf16 v[2:17], v[124:127], v[66:69], v[2:17]
	s_cbranch_scc1 .LBB0_1205

; #define MFMA(a, b, c) __builtin_amdgcn_mfma_f32_32x32x16_bf16((a), (b), (c), 0, 0, 0)
; __device__ __forceinline__ void toeplitz_item(const Params& p, int layer, int half, int c, bf16* sm, int dry, unsigned* done_ctr) {
;     ...
;       if (actv[0] && actv[1]) {
; #pragma unroll
;         for (int ks = 0; ks < 8; ++ks) {
;           const s8v a0 = *(const s8v*)(ap0 + 16 * ks), a1 = *(const s8v*)(ap0 - 32 + 16 * ks);
;           const s8v b0 = *(const s8v*)(bp0 + 16 * ks), b1 = *(const s8v*)(bp1 + 16 * ks);
;           acc[0][0] = MFMA(a0, b0, acc[0][0]);
;           acc[1][0] = MFMA(a1, b0, acc[1][0]);
;           acc[0][1] = MFMA(a0, b1, acc[0][1]);
;           acc[1][1] = MFMA(a1, b1, acc[1][1]);
;         }
.LBB0_1429:
	s_andn2_saveexec_b64 s[94:95], s[20:21]
	s_cbranch_execz .LBB0_1431
	v_add_u32_e32 v14, v106, v14
	s_waitcnt lgkmcnt(0)
	ds_read_b128 v[6:9], v14
	v_add_u32_e32 v15, v106, v15
	s_waitcnt lgkmcnt(0)
	v_mfma_f32_32x32x16_bf16 v[64:79], v[2:5], v[6:9], v[64:79]
	v_mfma_f32_32x32x16_bf16 v[32:47], v[84:87], v[6:9], v[32:47]
	ds_read_b128 v[6:9], v15
	s_waitcnt lgkmcnt(0)
	v_mfma_f32_32x32x16_bf16 v[48:63], v[2:5], v[6:9], v[48:63]
	v_mfma_f32_32x32x16_bf16 v[16:31], v[84:87], v[6:9], v[16:31]
	ds_read_b128 v[6:9], v108 offset:35120
	ds_read_b128 v[10:13], v14 offset:32
	ds_read_b128 v[80:83], v108 offset:35056
	s_waitcnt lgkmcnt(1)
	v_mfma_f32_32x32x16_bf16 v[64:79], v[6:9], v[10:13], v[64:79]
	s_waitcnt lgkmcnt(0)
	v_mfma_f32_32x32x16_bf16 v[32:47], v[80:83], v[10:13], v[32:47]
	ds_read_b128 v[10:13], v15 offset:32
	s_waitcnt lgkmcnt(0)
	v_mfma_f32_32x32x16_bf16 v[48:63], v[6:9], v[10:13], v[48:63]
	v_mfma_f32_32x32x16_bf16 v[16:31], v[80:83], v[10:13], v[16:31]
	ds_read_b128 v[80:83], v14 offset:64
	ds_read_b128 v[200:203], v15 offset:64
	ds_read_b128 v[10:13], v108 offset:35152
	ds_read_b128 v[204:207], v14 offset:96
	ds_read_b128 v[208:211], v15 offset:96
	s_waitcnt lgkmcnt(4)
	v_mfma_f32_32x32x16_bf16 v[32:47], v[2:5], v[80:83], v[32:47]
	s_waitcnt lgkmcnt(3)
	v_mfma_f32_32x32x16_bf16 v[16:31], v[2:5], v[200:203], v[16:31]
	ds_read_b128 v[2:5], v108 offset:35184
	s_waitcnt lgkmcnt(3)
	v_mfma_f32_32x32x16_bf16 v[64:79], v[10:13], v[80:83], v[64:79]
	v_mfma_f32_32x32x16_bf16 v[48:63], v[10:13], v[200:203], v[48:63]
	ds_read_b128 v[80:83], v14 offset:128
	ds_read_b128 v[200:203], v15 offset:128
	s_waitcnt lgkmcnt(4)
	v_mfma_f32_32x32x16_bf16 v[32:47], v[6:9], v[204:207], v[32:47]
	s_waitcnt lgkmcnt(3)
	v_mfma_f32_32x32x16_bf16 v[16:31], v[6:9], v[208:211], v[16:31]
	ds_read_b128 v[6:9], v108 offset:35216
	s_waitcnt lgkmcnt(3)
	v_mfma_f32_32x32x16_bf16 v[64:79], v[2:5], v[204:207], v[64:79]
	v_mfma_f32_32x32x16_bf16 v[48:63], v[2:5], v[208:211], v[48:63]
	ds_read_b128 v[204:207], v14 offset:160
	ds_read_b128 v[208:211], v15 offset:160
	s_waitcnt lgkmcnt(4)
	v_mfma_f32_32x32x16_bf16 v[32:47], v[10:13], v[80:83], v[32:47]
	s_waitcnt lgkmcnt(3)
	v_mfma_f32_32x32x16_bf16 v[16:31], v[10:13], v[200:203], v[16:31]
	ds_read_b128 v[10:13], v108 offset:35248
	s_waitcnt lgkmcnt(3)
	v_mfma_f32_32x32x16_bf16 v[64:79], v[6:9], v[80:83], v[64:79]
	v_mfma_f32_32x32x16_bf16 v[48:63], v[6:9], v[200:203], v[48:63]
	s_waitcnt lgkmcnt(2)
	v_mfma_f32_32x32x16_bf16 v[32:47], v[2:5], v[204:207], v[32:47]
	s_waitcnt lgkmcnt(1)
	v_mfma_f32_32x32x16_bf16 v[16:31], v[2:5], v[208:211], v[16:31]
	s_waitcnt lgkmcnt(0)
	v_mfma_f32_32x32x16_bf16 v[64:79], v[10:13], v[204:207], v[64:79]
	v_mfma_f32_32x32x16_bf16 v[48:63], v[10:13], v[208:211], v[48:63]
	ds_read_b128 v[80:83], v14 offset:192
	ds_read_b128 v[2:5], v108 offset:35280
	s_waitcnt lgkmcnt(1)
	v_mfma_f32_32x32x16_bf16 v[32:47], v[6:9], v[80:83], v[32:47]
	s_waitcnt lgkmcnt(0)
	v_mfma_f32_32x32x16_bf16 v[64:79], v[2:5], v[80:83], v[64:79]
	ds_read_b128 v[80:83], v15 offset:192
	s_waitcnt lgkmcnt(0)
	v_mfma_f32_32x32x16_bf16 v[48:63], v[2:5], v[80:83], v[48:63]
	v_mfma_f32_32x32x16_bf16 v[16:31], v[6:9], v[80:83], v[16:31]
	ds_read_b128 v[6:9], v14 offset:224
	ds_read_b128 v[2:5], v108 offset:35312
	s_waitcnt lgkmcnt(1)
	v_mfma_f32_32x32x16_bf16 v[32:47], v[10:13], v[6:9], v[32:47]
	s_waitcnt lgkmcnt(0)
	v_mfma_f32_32x32x16_bf16 v[64:79], v[2:5], v[6:9], v[64:79]
	ds_read_b128 v[6:9], v15 offset:224
	s_waitcnt lgkmcnt(0)
	v_mfma_f32_32x32x16_bf16 v[48:63], v[2:5], v[6:9], v[48:63]
	v_mfma_f32_32x32x16_bf16 v[16:31], v[10:13], v[6:9], v[16:31]

; #define MFMA(a, b, c) __builtin_amdgcn_mfma_f32_32x32x16_bf16((a), (b), (c), 0, 0, 0)
; __device__ __forceinline__ void toeplitz_item(const Params& p, int layer, int half, int c, bf16* sm, int dry, unsigned* done_ctr) {
;     ...
;       if (actv[0] && actv[1]) {
; #pragma unroll
;         for (int ks = 0; ks < 8; ++ks) {
;           const s8v a0 = *(const s8v*)(ap0 + 16 * ks), a1 = *(const s8v*)(ap0 - 32 + 16 * ks);
;           const s8v b0 = *(const s8v*)(bp0 + 16 * ks), b1 = *(const s8v*)(bp1 + 16 * ks);
;           acc[0][0] = MFMA(a0, b0, acc[0][0]);
;           acc[1][0] = MFMA(a1, b0, acc[1][0]);
;           acc[0][1] = MFMA(a0, b1, acc[0][1]);
;           acc[1][1] = MFMA(a1, b1, acc[1][1]);
;         }
.LBB0_1439:
	s_andn2_saveexec_b64 s[20:21], s[20:21]
	s_cbranch_execz .LBB0_1441
	v_add_u32_e32 v14, v106, v14
	s_waitcnt lgkmcnt(0)
	ds_read_b128 v[6:9], v14
	v_add_u32_e32 v15, v106, v15
	s_waitcnt lgkmcnt(0)
	v_mfma_f32_32x32x16_bf16 v[64:79], v[2:5], v[6:9], v[64:79]
	v_mfma_f32_32x32x16_bf16 v[32:47], v[84:87], v[6:9], v[32:47]
	ds_read_b128 v[6:9], v15
	s_waitcnt lgkmcnt(0)
	v_mfma_f32_32x32x16_bf16 v[48:63], v[2:5], v[6:9], v[48:63]
	v_mfma_f32_32x32x16_bf16 v[16:31], v[84:87], v[6:9], v[16:31]
	ds_read_b128 v[6:9], v108 offset:34864
	ds_read_b128 v[10:13], v14 offset:32
	ds_read_b128 v[80:83], v108 offset:34800
	s_waitcnt lgkmcnt(1)
	v_mfma_f32_32x32x16_bf16 v[64:79], v[6:9], v[10:13], v[64:79]
	s_waitcnt lgkmcnt(0)
	v_mfma_f32_32x32x16_bf16 v[32:47], v[80:83], v[10:13], v[32:47]
	ds_read_b128 v[10:13], v15 offset:32
	s_waitcnt lgkmcnt(0)
	v_mfma_f32_32x32x16_bf16 v[48:63], v[6:9], v[10:13], v[48:63]
	v_mfma_f32_32x32x16_bf16 v[16:31], v[80:83], v[10:13], v[16:31]
	ds_read_b128 v[80:83], v14 offset:64
	ds_read_b128 v[200:203], v15 offset:64
	ds_read_b128 v[10:13], v108 offset:34896
	ds_read_b128 v[204:207], v14 offset:96
	ds_read_b128 v[208:211], v15 offset:96
	s_waitcnt lgkmcnt(4)
	v_mfma_f32_32x32x16_bf16 v[32:47], v[2:5], v[80:83], v[32:47]
	s_waitcnt lgkmcnt(3)
	v_mfma_f32_32x32x16_bf16 v[16:31], v[2:5], v[200:203], v[16:31]
	ds_read_b128 v[2:5], v108 offset:34928
	s_waitcnt lgkmcnt(3)
	v_mfma_f32_32x32x16_bf16 v[64:79], v[10:13], v[80:83], v[64:79]
	v_mfma_f32_32x32x16_bf16 v[48:63], v[10:13], v[200:203], v[48:63]
	ds_read_b128 v[80:83], v14 offset:128
	ds_read_b128 v[200:203], v15 offset:128
	s_waitcnt lgkmcnt(4)
	v_mfma_f32_32x32x16_bf16 v[32:47], v[6:9], v[204:207], v[32:47]
	s_waitcnt lgkmcnt(3)
	v_mfma_f32_32x32x16_bf16 v[16:31], v[6:9], v[208:211], v[16:31]
	ds_read_b128 v[6:9], v108 offset:34960
	s_waitcnt lgkmcnt(3)
	v_mfma_f32_32x32x16_bf16 v[64:79], v[2:5], v[204:207], v[64:79]
	v_mfma_f32_32x32x16_bf16 v[48:63], v[2:5], v[208:211], v[48:63]
	ds_read_b128 v[204:207], v14 offset:160
	ds_read_b128 v[208:211], v15 offset:160
	s_waitcnt lgkmcnt(4)
	v_mfma_f32_32x32x16_bf16 v[32:47], v[10:13], v[80:83], v[32:47]
	s_waitcnt lgkmcnt(3)
	v_mfma_f32_32x32x16_bf16 v[16:31], v[10:13], v[200:203], v[16:31]
	ds_read_b128 v[10:13], v108 offset:34992
	s_waitcnt lgkmcnt(3)
	v_mfma_f32_32x32x16_bf16 v[64:79], v[6:9], v[80:83], v[64:79]
	v_mfma_f32_32x32x16_bf16 v[48:63], v[6:9], v[200:203], v[48:63]
	s_waitcnt lgkmcnt(2)
	v_mfma_f32_32x32x16_bf16 v[32:47], v[2:5], v[204:207], v[32:47]
	s_waitcnt lgkmcnt(1)
	v_mfma_f32_32x32x16_bf16 v[16:31], v[2:5], v[208:211], v[16:31]
	s_waitcnt lgkmcnt(0)
	v_mfma_f32_32x32x16_bf16 v[64:79], v[10:13], v[204:207], v[64:79]
	v_mfma_f32_32x32x16_bf16 v[48:63], v[10:13], v[208:211], v[48:63]
	ds_read_b128 v[80:83], v14 offset:192
	ds_read_b128 v[2:5], v108 offset:35024
	s_waitcnt lgkmcnt(1)
	v_mfma_f32_32x32x16_bf16 v[32:47], v[6:9], v[80:83], v[32:47]
	s_waitcnt lgkmcnt(0)
	v_mfma_f32_32x32x16_bf16 v[64:79], v[2:5], v[80:83], v[64:79]
	ds_read_b128 v[80:83], v15 offset:192
	s_waitcnt lgkmcnt(0)
	v_mfma_f32_32x32x16_bf16 v[48:63], v[2:5], v[80:83], v[48:63]
	v_mfma_f32_32x32x16_bf16 v[16:31], v[6:9], v[80:83], v[16:31]
	ds_read_b128 v[6:9], v14 offset:224
	ds_read_b128 v[2:5], v108 offset:35056
	s_waitcnt lgkmcnt(1)
	v_mfma_f32_32x32x16_bf16 v[32:47], v[10:13], v[6:9], v[32:47]
	s_waitcnt lgkmcnt(0)
	v_mfma_f32_32x32x16_bf16 v[64:79], v[2:5], v[6:9], v[64:79]
	ds_read_b128 v[6:9], v15 offset:224
	s_waitcnt lgkmcnt(0)
	v_mfma_f32_32x32x16_bf16 v[48:63], v[2:5], v[6:9], v[48:63]
	v_mfma_f32_32x32x16_bf16 v[16:31], v[10:13], v[6:9], v[16:31]

; #define MFMA(a, b, c) __builtin_amdgcn_mfma_f32_32x32x16_bf16((a), (b), (c), 0, 0, 0)
; __device__ __forceinline__ void toeplitz_item(const Params& p, int layer, int half, int c, bf16* sm, int dry, unsigned* done_ctr) {
;     ...
;       if (actv[0] && actv[1]) {
; #pragma unroll
;         for (int ks = 0; ks < 8; ++ks) {
;           const s8v a0 = *(const s8v*)(ap0 + 16 * ks), a1 = *(const s8v*)(ap0 - 32 + 16 * ks);
;           const s8v b0 = *(const s8v*)(bp0 + 16 * ks), b1 = *(const s8v*)(bp1 + 16 * ks);
;           acc[0][0] = MFMA(a0, b0, acc[0][0]);
;           acc[1][0] = MFMA(a1, b0, acc[1][0]);
;           acc[0][1] = MFMA(a0, b1, acc[0][1]);
;           acc[1][1] = MFMA(a1, b1, acc[1][1]);
;         }
.LBB0_1449:
	s_andn2_saveexec_b64 s[20:21], s[20:21]
	s_cbranch_execz .LBB0_1451
	v_add_u32_e32 v14, v106, v14
	s_waitcnt lgkmcnt(0)
	ds_read_b128 v[6:9], v14
	v_add_u32_e32 v15, v106, v15
	s_waitcnt lgkmcnt(0)
	v_mfma_f32_32x32x16_bf16 v[64:79], v[2:5], v[6:9], v[64:79]
	v_mfma_f32_32x32x16_bf16 v[32:47], v[84:87], v[6:9], v[32:47]
	ds_read_b128 v[6:9], v15
	s_waitcnt lgkmcnt(0)
	v_mfma_f32_32x32x16_bf16 v[48:63], v[2:5], v[6:9], v[48:63]
	v_mfma_f32_32x32x16_bf16 v[16:31], v[84:87], v[6:9], v[16:31]
	ds_read_b128 v[6:9], v108 offset:34608
	ds_read_b128 v[10:13], v14 offset:32
	ds_read_b128 v[80:83], v108 offset:34544
	s_waitcnt lgkmcnt(1)
	v_mfma_f32_32x32x16_bf16 v[64:79], v[6:9], v[10:13], v[64:79]
	s_waitcnt lgkmcnt(0)
	v_mfma_f32_32x32x16_bf16 v[32:47], v[80:83], v[10:13], v[32:47]
	ds_read_b128 v[10:13], v15 offset:32
	s_waitcnt lgkmcnt(0)
	v_mfma_f32_32x32x16_bf16 v[48:63], v[6:9], v[10:13], v[48:63]
	v_mfma_f32_32x32x16_bf16 v[16:31], v[80:83], v[10:13], v[16:31]
	ds_read_b128 v[80:83], v14 offset:64
	ds_read_b128 v[200:203], v15 offset:64
	ds_read_b128 v[10:13], v108 offset:34640
	ds_read_b128 v[204:207], v14 offset:96
	ds_read_b128 v[208:211], v15 offset:96
	s_waitcnt lgkmcnt(4)
	v_mfma_f32_32x32x16_bf16 v[32:47], v[2:5], v[80:83], v[32:47]
	s_waitcnt lgkmcnt(3)
	v_mfma_f32_32x32x16_bf16 v[16:31], v[2:5], v[200:203], v[16:31]
	ds_read_b128 v[2:5], v108 offset:34672
	s_waitcnt lgkmcnt(3)
	v_mfma_f32_32x32x16_bf16 v[64:79], v[10:13], v[80:83], v[64:79]
	v_mfma_f32_32x32x16_bf16 v[48:63], v[10:13], v[200:203], v[48:63]
	ds_read_b128 v[80:83], v14 offset:128
	ds_read_b128 v[200:203], v15 offset:128
	s_waitcnt lgkmcnt(4)
	v_mfma_f32_32x32x16_bf16 v[32:47], v[6:9], v[204:207], v[32:47]
	s_waitcnt lgkmcnt(3)
	v_mfma_f32_32x32x16_bf16 v[16:31], v[6:9], v[208:211], v[16:31]
	ds_read_b128 v[6:9], v108 offset:34704
	s_waitcnt lgkmcnt(3)
	v_mfma_f32_32x32x16_bf16 v[64:79], v[2:5], v[204:207], v[64:79]
	v_mfma_f32_32x32x16_bf16 v[48:63], v[2:5], v[208:211], v[48:63]
	ds_read_b128 v[204:207], v14 offset:160
	ds_read_b128 v[208:211], v15 offset:160
	s_waitcnt lgkmcnt(4)
	v_mfma_f32_32x32x16_bf16 v[32:47], v[10:13], v[80:83], v[32:47]
	s_waitcnt lgkmcnt(3)
	v_mfma_f32_32x32x16_bf16 v[16:31], v[10:13], v[200:203], v[16:31]
	ds_read_b128 v[10:13], v108 offset:34736
	s_waitcnt lgkmcnt(3)
	v_mfma_f32_32x32x16_bf16 v[64:79], v[6:9], v[80:83], v[64:79]
	v_mfma_f32_32x32x16_bf16 v[48:63], v[6:9], v[200:203], v[48:63]
	s_waitcnt lgkmcnt(2)
	v_mfma_f32_32x32x16_bf16 v[32:47], v[2:5], v[204:207], v[32:47]
	s_waitcnt lgkmcnt(1)
	v_mfma_f32_32x32x16_bf16 v[16:31], v[2:5], v[208:211], v[16:31]
	s_waitcnt lgkmcnt(0)
	v_mfma_f32_32x32x16_bf16 v[64:79], v[10:13], v[204:207], v[64:79]
	v_mfma_f32_32x32x16_bf16 v[48:63], v[10:13], v[208:211], v[48:63]
	ds_read_b128 v[80:83], v14 offset:192
	ds_read_b128 v[2:5], v108 offset:34768
	s_waitcnt lgkmcnt(1)
	v_mfma_f32_32x32x16_bf16 v[32:47], v[6:9], v[80:83], v[32:47]
	s_waitcnt lgkmcnt(0)
	v_mfma_f32_32x32x16_bf16 v[64:79], v[2:5], v[80:83], v[64:79]
	ds_read_b128 v[80:83], v15 offset:192
	s_waitcnt lgkmcnt(0)
	v_mfma_f32_32x32x16_bf16 v[48:63], v[2:5], v[80:83], v[48:63]
	v_mfma_f32_32x32x16_bf16 v[16:31], v[6:9], v[80:83], v[16:31]
	ds_read_b128 v[6:9], v14 offset:224
	ds_read_b128 v[2:5], v108 offset:34800
	s_waitcnt lgkmcnt(1)
	v_mfma_f32_32x32x16_bf16 v[32:47], v[10:13], v[6:9], v[32:47]
	s_waitcnt lgkmcnt(0)
	v_mfma_f32_32x32x16_bf16 v[64:79], v[2:5], v[6:9], v[64:79]
	ds_read_b128 v[6:9], v15 offset:224
	s_waitcnt lgkmcnt(0)
	v_mfma_f32_32x32x16_bf16 v[48:63], v[2:5], v[6:9], v[48:63]
	v_mfma_f32_32x32x16_bf16 v[16:31], v[10:13], v[6:9], v[16:31]

; #define MFMA(a, b, c) __builtin_amdgcn_mfma_f32_32x32x16_bf16((a), (b), (c), 0, 0, 0)
; __device__ __forceinline__ void toeplitz_item(const Params& p, int layer, int half, int c, bf16* sm, int dry, unsigned* done_ctr) {
;     ...
;       if (actv[0] && actv[1]) {
; #pragma unroll
;         for (int ks = 0; ks < 8; ++ks) {
;           const s8v a0 = *(const s8v*)(ap0 + 16 * ks), a1 = *(const s8v*)(ap0 - 32 + 16 * ks);
;           const s8v b0 = *(const s8v*)(bp0 + 16 * ks), b1 = *(const s8v*)(bp1 + 16 * ks);
;           acc[0][0] = MFMA(a0, b0, acc[0][0]);
;           acc[1][0] = MFMA(a1, b0, acc[1][0]);
;           acc[0][1] = MFMA(a0, b1, acc[0][1]);
;           acc[1][1] = MFMA(a1, b1, acc[1][1]);
;         }
.LBB0_1459:
	s_andn2_saveexec_b64 s[20:21], s[20:21]
	s_cbranch_execz .LBB0_1369
	v_add_u32_e32 v0, v106, v0
	s_waitcnt lgkmcnt(0)
	ds_read_b128 v[6:9], v0
	v_add_u32_e32 v14, v106, v14
	s_waitcnt lgkmcnt(0)
	v_mfma_f32_32x32x16_bf16 v[64:79], v[2:5], v[6:9], v[64:79]
	v_mfma_f32_32x32x16_bf16 v[32:47], v[84:87], v[6:9], v[32:47]
	ds_read_b128 v[6:9], v14
	s_waitcnt lgkmcnt(0)
	v_mfma_f32_32x32x16_bf16 v[48:63], v[2:5], v[6:9], v[48:63]
	v_mfma_f32_32x32x16_bf16 v[16:31], v[84:87], v[6:9], v[16:31]
	ds_read_b128 v[6:9], v108 offset:34352
	ds_read_b128 v[10:13], v0 offset:32
	ds_read_b128 v[80:83], v108 offset:34288
	s_waitcnt lgkmcnt(1)
	v_mfma_f32_32x32x16_bf16 v[64:79], v[6:9], v[10:13], v[64:79]
	s_waitcnt lgkmcnt(0)
	v_mfma_f32_32x32x16_bf16 v[32:47], v[80:83], v[10:13], v[32:47]
	ds_read_b128 v[10:13], v14 offset:32
	s_waitcnt lgkmcnt(0)
	v_mfma_f32_32x32x16_bf16 v[48:63], v[6:9], v[10:13], v[48:63]
	v_mfma_f32_32x32x16_bf16 v[16:31], v[80:83], v[10:13], v[16:31]
	ds_read_b128 v[80:83], v0 offset:64
	ds_read_b128 v[200:203], v14 offset:64
	ds_read_b128 v[10:13], v108 offset:34384
	ds_read_b128 v[204:207], v0 offset:96
	ds_read_b128 v[208:211], v14 offset:96
	s_waitcnt lgkmcnt(4)
	v_mfma_f32_32x32x16_bf16 v[32:47], v[2:5], v[80:83], v[32:47]
	s_waitcnt lgkmcnt(3)
	v_mfma_f32_32x32x16_bf16 v[16:31], v[2:5], v[200:203], v[16:31]
	ds_read_b128 v[2:5], v108 offset:34416
	s_waitcnt lgkmcnt(3)
	v_mfma_f32_32x32x16_bf16 v[64:79], v[10:13], v[80:83], v[64:79]
	v_mfma_f32_32x32x16_bf16 v[48:63], v[10:13], v[200:203], v[48:63]
	ds_read_b128 v[80:83], v0 offset:128
	ds_read_b128 v[200:203], v14 offset:128
	s_waitcnt lgkmcnt(4)
	v_mfma_f32_32x32x16_bf16 v[32:47], v[6:9], v[204:207], v[32:47]
	s_waitcnt lgkmcnt(3)
	v_mfma_f32_32x32x16_bf16 v[16:31], v[6:9], v[208:211], v[16:31]
	ds_read_b128 v[6:9], v108 offset:34448
	s_waitcnt lgkmcnt(3)
	v_mfma_f32_32x32x16_bf16 v[64:79], v[2:5], v[204:207], v[64:79]
	v_mfma_f32_32x32x16_bf16 v[48:63], v[2:5], v[208:211], v[48:63]
	ds_read_b128 v[204:207], v0 offset:160
	ds_read_b128 v[208:211], v14 offset:160
	s_waitcnt lgkmcnt(4)
	v_mfma_f32_32x32x16_bf16 v[32:47], v[10:13], v[80:83], v[32:47]
	s_waitcnt lgkmcnt(3)
	v_mfma_f32_32x32x16_bf16 v[16:31], v[10:13], v[200:203], v[16:31]
	ds_read_b128 v[10:13], v108 offset:34480
	s_waitcnt lgkmcnt(3)
	v_mfma_f32_32x32x16_bf16 v[64:79], v[6:9], v[80:83], v[64:79]
	v_mfma_f32_32x32x16_bf16 v[48:63], v[6:9], v[200:203], v[48:63]
	s_waitcnt lgkmcnt(2)
	v_mfma_f32_32x32x16_bf16 v[32:47], v[2:5], v[204:207], v[32:47]
	s_waitcnt lgkmcnt(1)
	v_mfma_f32_32x32x16_bf16 v[16:31], v[2:5], v[208:211], v[16:31]
	s_waitcnt lgkmcnt(0)
	v_mfma_f32_32x32x16_bf16 v[64:79], v[10:13], v[204:207], v[64:79]
	v_mfma_f32_32x32x16_bf16 v[48:63], v[10:13], v[208:211], v[48:63]
	ds_read_b128 v[80:83], v0 offset:192
	ds_read_b128 v[2:5], v108 offset:34512
	s_waitcnt lgkmcnt(1)
	v_mfma_f32_32x32x16_bf16 v[32:47], v[6:9], v[80:83], v[32:47]
	s_waitcnt lgkmcnt(0)
	v_mfma_f32_32x32x16_bf16 v[64:79], v[2:5], v[80:83], v[64:79]
	ds_read_b128 v[80:83], v14 offset:192
	s_waitcnt lgkmcnt(0)
	v_mfma_f32_32x32x16_bf16 v[48:63], v[2:5], v[80:83], v[48:63]
	v_mfma_f32_32x32x16_bf16 v[16:31], v[6:9], v[80:83], v[16:31]
	ds_read_b128 v[6:9], v0 offset:224
	ds_read_b128 v[2:5], v108 offset:34544
	s_waitcnt lgkmcnt(1)
	v_mfma_f32_32x32x16_bf16 v[32:47], v[10:13], v[6:9], v[32:47]
	s_waitcnt lgkmcnt(0)
	v_mfma_f32_32x32x16_bf16 v[64:79], v[2:5], v[6:9], v[64:79]
	ds_read_b128 v[6:9], v14 offset:224
	s_waitcnt lgkmcnt(0)
	v_mfma_f32_32x32x16_bf16 v[48:63], v[2:5], v[6:9], v[48:63]
	v_mfma_f32_32x32x16_bf16 v[16:31], v[10:13], v[6:9], v[16:31]
	s_branch .LBB0_1369
